# v20 plus P4/P6 epilogue loads (and address setup) issued at the end of the unit's last K-loop trip, before the trailing barrier and ALIGN rendezvous
# baseline (speedup 1.0000x reference)
;     __device__ __forceinline__ void mid(f32x4 (&acc)[2][2][4][2], const Unit& u, int wr, int wc, int fr, int fq) const { scale(acc, u, wr, wc, fr, fq, 0); }
; #define PG8_STAGE(bufoff, gbase, voff) do { _Pragma("unroll") for (int _i = 0; _i < 2; ++_i) \
;         __builtin_amdgcn_global_load_lds((const unsigned*)((const char*)(gbase) + (voff)[_i]), (PG8_LAS unsigned*)(lds + (bufoff) + ldsw + _i * 8192), 16, 0, 0); } while (0)
; #define PG8_LDA(dst, b, h) do { _Pragma("unroll") for (int m = 0; m < 4; ++m) _Pragma("unroll") for (int k = 0; k < 2; ++k) dst[m][k] = *(const PG8_LAS bf16x8*)(lds + PG8_SA(b, h) + aoff + m * 2048 + k * 1024); } while (0)
; #define PG8_LDB(dst, b, h) do { _Pragma("unroll") for (int n = 0; n < 2; ++n) _Pragma("unroll") for (int k = 0; k < 2; ++k) dst[n][k] = *(const PG8_LAS bf16x8*)(lds + PG8_SB(b, h) + boff + n * 2048 + k * 1024); } while (0)
; #define PG8_WAIT_V(n) asm volatile("s_waitcnt vmcnt(" #n ")" ::: "memory")
; #define PG8_WAIT_L(n) asm volatile("s_waitcnt lgkmcnt(" #n ")" ::: "memory")
; template <class Epi, class Sched, bool ALIGN_EPI = false, bool SP2 = false>
; __device__ __forceinline__ void gemm_phase(PG8_LAS unsigned char* lds, const Gemm g, const Sched& S, const Epi& E, const int wave_s) {
;     ...
;         for (int t = 0; t < nt; t += 2) {
;             if constexpr (Epi::MIDK > 0) { if (t == Epi::MIDK) E.mid(acc, cur, wr, wc, fr, fq); }
;             const bool last = (t == nt - 2);
;             if constexpr (Epi::HAS_PRE) { if (last) E.pre(cur, wr, fr, pf); }
;             const char* a1 = cA + (size_t)(t + 1) * kstep;
;             const char* a2 = last ? nA : cA + (size_t)(t + 2) * kstep; const char* b2 = last ? nB : cB + (size_t)(t + 2) * kstep;
;             const char* a3 = a2 + kstep; const char* b3 = b2 + kstep;
;             if (last && has_next) S.a_ready(nxt);
;             if constexpr (SP2) {
;             PG8_LDB(B0, 0, 0); PG8_LDB(B1, 0, 1); PG8_SCHED; PG8_LDA(At, 0, 0); PG8_STAGE(PG8_SA(1, 1), a1 + hA, voffA);
;             PG8_WAIT_V(8); PG8_WAIT_L(0); PG8_BAR; PG8_MMA(0, 0, At, B0); PG8_MMA(0, 1, At, B1); PG8_BAR; PG8_SCHED;
;             PG8_LDA(At, 0, 1); PG8_STAGE(PG8_SB(0, 0), b2, voffB); PG8_STAGE(PG8_SB(0, 1), b2 + hB, voffB); PG8_STAGE(PG8_SA(0, 0), a2, voffA);
;             PG8_WAIT_V(8); PG8_WAIT_L(0); PG8_BAR; PG8_MMA(1, 0, At, B0); PG8_MMA(1, 1, At, B1); PG8_BAR; PG8_SCHED;
.LBB0_696:
	ds_read_b128 v[144:147], v155
	ds_read_b128 v[148:151], v155 offset:1024
	ds_read_b128 v[158:161], v155 offset:2048
	ds_read_b128 v[162:165], v155 offset:3072
	ds_read_b128 v[166:169], v156
	ds_read_b128 v[170:173], v156 offset:1024
	ds_read_b128 v[174:177], v156 offset:2048
	ds_read_b128 v[178:181], v156 offset:3072
	s_add_u32 s66, s64, 0xfffc0080
	s_addc_u32 s67, s65, -1
	s_cmp_eq_u32 s78, 12
	s_cselect_b32 s69, s8, s67
	s_cselect_b32 s68, s9, s66
	s_cselect_b32 s67, s47, s77
	s_cselect_b32 s66, s49, s61
	v_lshl_add_u64 v[218:219], s[64:65], 0, v[136:137]
	s_add_i32 m0, s12, 0xc000
	ds_read_b128 v[182:185], v157
	ds_read_b128 v[186:189], v157 offset:1024
	ds_read_b128 v[190:193], v157 offset:2048
	ds_read_b128 v[194:197], v157 offset:3072
	ds_read_b128 v[198:201], v157 offset:4096
	ds_read_b128 v[202:205], v157 offset:5120
	ds_read_b128 v[206:209], v157 offset:6144
	ds_read_b128 v[210:213], v157 offset:7168
	global_load_lds_dwordx4 v[218:219], off
	v_lshl_add_u64 v[218:219], s[64:65], 0, v[138:139]
	s_add_i32 m0, s12, 0xe000
	s_nop 0
	global_load_lds_dwordx4 v[218:219], off
	s_waitcnt vmcnt(8)
	s_waitcnt lgkmcnt(0)
	s_barrier
	s_setprio 1
	s_waitcnt lgkmcnt(0)
	v_mfma_f32_16x16x32_bf16 v[124:127], v[144:147], v[182:185], v[124:127]
	v_mfma_f32_16x16x32_bf16 v[120:123], v[158:161], v[182:185], v[120:123]
	v_mfma_f32_16x16x32_bf16 v[108:111], v[144:147], v[190:193], v[108:111]
	v_mfma_f32_16x16x32_bf16 v[104:107], v[158:161], v[190:193], v[104:107]
	v_mfma_f32_16x16x32_bf16 v[92:95], v[144:147], v[198:201], v[92:95]
	v_mfma_f32_16x16x32_bf16 v[88:91], v[158:161], v[198:201], v[88:91]
	v_mfma_f32_16x16x32_bf16 v[76:79], v[144:147], v[206:209], v[76:79]
	v_mfma_f32_16x16x32_bf16 v[72:75], v[158:161], v[206:209], v[72:75]
	v_mfma_f32_16x16x32_bf16 v[124:127], v[148:151], v[186:189], v[124:127]
	v_mfma_f32_16x16x32_bf16 v[120:123], v[162:165], v[186:189], v[120:123]
	v_mfma_f32_16x16x32_bf16 v[108:111], v[148:151], v[194:197], v[108:111]
	v_mfma_f32_16x16x32_bf16 v[104:107], v[162:165], v[194:197], v[104:107]
	v_mfma_f32_16x16x32_bf16 v[92:95], v[148:151], v[202:205], v[92:95]
	v_mfma_f32_16x16x32_bf16 v[88:91], v[162:165], v[202:205], v[88:91]
	v_mfma_f32_16x16x32_bf16 v[76:79], v[148:151], v[210:213], v[76:79]
	v_mfma_f32_16x16x32_bf16 v[72:75], v[162:165], v[210:213], v[72:75]
	s_setprio 0
	s_setprio 1
	v_mfma_f32_16x16x32_bf16 v[116:119], v[166:169], v[182:185], v[116:119]
	v_mfma_f32_16x16x32_bf16 v[112:115], v[174:177], v[182:185], v[112:115]
	v_mfma_f32_16x16x32_bf16 v[100:103], v[166:169], v[190:193], v[100:103]
	v_mfma_f32_16x16x32_bf16 v[96:99], v[174:177], v[190:193], v[96:99]
	v_mfma_f32_16x16x32_bf16 v[84:87], v[166:169], v[198:201], v[84:87]
	v_mfma_f32_16x16x32_bf16 v[80:83], v[174:177], v[198:201], v[80:83]
	v_mfma_f32_16x16x32_bf16 v[68:71], v[166:169], v[206:209], v[68:71]
	v_mfma_f32_16x16x32_bf16 v[64:67], v[174:177], v[206:209], v[64:67]
	v_mfma_f32_16x16x32_bf16 v[116:119], v[170:173], v[186:189], v[116:119]
	v_mfma_f32_16x16x32_bf16 v[112:115], v[178:181], v[186:189], v[112:115]
	v_mfma_f32_16x16x32_bf16 v[100:103], v[170:173], v[194:197], v[100:103]
	v_mfma_f32_16x16x32_bf16 v[96:99], v[178:181], v[194:197], v[96:99]
	v_mfma_f32_16x16x32_bf16 v[84:87], v[170:173], v[202:205], v[84:87]
	v_mfma_f32_16x16x32_bf16 v[80:83], v[178:181], v[202:205], v[80:83]
	v_mfma_f32_16x16x32_bf16 v[68:71], v[170:173], v[210:213], v[68:71]
	v_mfma_f32_16x16x32_bf16 v[64:67], v[178:181], v[210:213], v[64:67]
	s_setprio 0
	s_barrier
	s_add_i32 s79, s75, s11
	v_lshl_add_u64 v[218:219], s[66:67], 0, v[130:131]
	s_mov_b32 m0, s79
	ds_read_b128 v[182:185], v157 offset:16384
	ds_read_b128 v[186:189], v157 offset:17408
	ds_read_b128 v[190:193], v157 offset:18432
	ds_read_b128 v[194:197], v157 offset:19456
	ds_read_b128 v[198:201], v157 offset:20480
	ds_read_b128 v[202:205], v157 offset:21504
	ds_read_b128 v[206:209], v157 offset:22528
	ds_read_b128 v[210:213], v157 offset:23552
	global_load_lds_dwordx4 v[218:219], off
	s_add_i32 m0, s79, 0x2000
	s_add_u32 s80, s66, 0x40000
	v_lshl_add_u64 v[220:221], s[66:67], 0, v[134:135]
	s_addc_u32 s81, s67, 0
	s_add_i32 s79, s76, s11
	global_load_lds_dwordx4 v[220:221], off
	v_lshl_add_u64 v[222:223], s[80:81], 0, v[130:131]
	s_mov_b32 m0, s79
	v_lshl_add_u64 v[224:225], s[68:69], 0, v[132:133]
	global_load_lds_dwordx4 v[222:223], off
	v_lshl_add_u64 v[222:223], s[80:81], 0, v[134:135]
	s_add_i32 m0, s79, 0x2000
	s_nop 0
	global_load_lds_dwordx4 v[222:223], off
	v_lshl_add_u64 v[222:223], s[68:69], 0, v[128:129]
	s_mov_b32 m0, s12
	s_nop 0
	global_load_lds_dwordx4 v[222:223], off
	s_mov_b32 m0, s13
	s_nop 0
	global_load_lds_dwordx4 v[224:225], off
	s_waitcnt vmcnt(8)
	s_waitcnt lgkmcnt(0)
	s_barrier
; #define PG8_STAGE(bufoff, gbase, voff) do { _Pragma("unroll") for (int _i = 0; _i < 2; ++_i) \
;         __builtin_amdgcn_global_load_lds((const unsigned*)((const char*)(gbase) + (voff)[_i]), (PG8_LAS unsigned*)(lds + (bufoff) + ldsw + _i * 8192), 16, 0, 0); } while (0)
; #define PG8_LDA(dst, b, h) do { _Pragma("unroll") for (int m = 0; m < 4; ++m) _Pragma("unroll") for (int k = 0; k < 2; ++k) dst[m][k] = *(const PG8_LAS bf16x8*)(lds + PG8_SA(b, h) + aoff + m * 2048 + k * 1024); } while (0)
; #define PG8_LDB(dst, b, h) do { _Pragma("unroll") for (int n = 0; n < 2; ++n) _Pragma("unroll") for (int k = 0; k < 2; ++k) dst[n][k] = *(const PG8_LAS bf16x8*)(lds + PG8_SB(b, h) + boff + n * 2048 + k * 1024); } while (0)
; #define PG8_MMA(ai, bj, At, Bt) do { __builtin_amdgcn_s_setprio(1); _Pragma("unroll") for (int m = 0; m < 4; ++m) _Pragma("unroll") for (int n = 0; n < 2; ++n) _Pragma("unroll") for (int k = 0; k < 2; ++k) \
;         acc[ai][bj][m][n] = __builtin_amdgcn_mfma_f32_16x16x32_bf16(Bt[n][k], At[m][k], acc[ai][bj][m][n], 0, 0, 0); __builtin_amdgcn_s_setprio(0); } while (0)
; #define PG8_WAIT_V(n) asm volatile("s_waitcnt vmcnt(" #n ")" ::: "memory")
; #define PG8_WAIT_L(n) asm volatile("s_waitcnt lgkmcnt(" #n ")" ::: "memory")
; #define PG8_BAR __builtin_amdgcn_s_barrier()
; #define PG8_SCHED __builtin_amdgcn_sched_barrier(0)
; template <class Epi, class Sched, bool ALIGN_EPI = false, bool SP2 = false>
; __device__ __forceinline__ void gemm_phase(PG8_LAS unsigned char* lds, const Gemm g, const Sched& S, const Epi& E, const int wave_s) {
;     ...
;             PG8_WAIT_V(8); PG8_WAIT_L(0); PG8_BAR; PG8_MMA(1, 0, At, B0); PG8_MMA(1, 1, At, B1); PG8_BAR; PG8_SCHED;
;             PG8_LDB(B0, 1, 0); PG8_LDB(B1, 1, 1); PG8_SCHED; PG8_LDA(At, 1, 0); PG8_STAGE(PG8_SA(0, 1), a2 + hA, voffA);
;             PG8_WAIT_V(8); PG8_WAIT_L(0); PG8_BAR; PG8_MMA(0, 0, At, B0); PG8_MMA(0, 1, At, B1); PG8_BAR; PG8_SCHED;
	s_setprio 1
	s_waitcnt lgkmcnt(0)
	v_mfma_f32_16x16x32_bf16 v[60:63], v[144:147], v[182:185], v[60:63]
	v_mfma_f32_16x16x32_bf16 v[56:59], v[158:161], v[182:185], v[56:59]
	v_mfma_f32_16x16x32_bf16 v[44:47], v[144:147], v[190:193], v[44:47]
	v_mfma_f32_16x16x32_bf16 v[40:43], v[158:161], v[190:193], v[40:43]
	v_mfma_f32_16x16x32_bf16 v[28:31], v[144:147], v[198:201], v[28:31]
	v_mfma_f32_16x16x32_bf16 v[24:27], v[158:161], v[198:201], v[24:27]
	v_mfma_f32_16x16x32_bf16 v[12:15], v[144:147], v[206:209], v[12:15]
	v_mfma_f32_16x16x32_bf16 v[8:11], v[158:161], v[206:209], v[8:11]
	v_mfma_f32_16x16x32_bf16 v[60:63], v[148:151], v[186:189], v[60:63]
	v_mfma_f32_16x16x32_bf16 v[56:59], v[162:165], v[186:189], v[56:59]
	v_mfma_f32_16x16x32_bf16 v[44:47], v[148:151], v[194:197], v[44:47]
	v_mfma_f32_16x16x32_bf16 v[40:43], v[162:165], v[194:197], v[40:43]
	v_mfma_f32_16x16x32_bf16 v[28:31], v[148:151], v[202:205], v[28:31]
	v_mfma_f32_16x16x32_bf16 v[24:27], v[162:165], v[202:205], v[24:27]
	v_mfma_f32_16x16x32_bf16 v[12:15], v[148:151], v[210:213], v[12:15]
	v_mfma_f32_16x16x32_bf16 v[8:11], v[162:165], v[210:213], v[8:11]
	s_setprio 0
	s_setprio 1
	v_mfma_f32_16x16x32_bf16 v[52:55], v[166:169], v[182:185], v[52:55]
	v_mfma_f32_16x16x32_bf16 v[48:51], v[174:177], v[182:185], v[48:51]
	v_mfma_f32_16x16x32_bf16 v[36:39], v[166:169], v[190:193], v[36:39]
	v_mfma_f32_16x16x32_bf16 v[32:35], v[174:177], v[190:193], v[32:35]
	v_mfma_f32_16x16x32_bf16 v[20:23], v[166:169], v[198:201], v[20:23]
	v_mfma_f32_16x16x32_bf16 v[16:19], v[174:177], v[198:201], v[16:19]
	v_mfma_f32_16x16x32_bf16 v[4:7], v[166:169], v[206:209], v[4:7]
	v_mfma_f32_16x16x32_bf16 v[0:3], v[174:177], v[206:209], v[0:3]
	v_mfma_f32_16x16x32_bf16 v[52:55], v[170:173], v[186:189], v[52:55]
	v_mfma_f32_16x16x32_bf16 v[48:51], v[178:181], v[186:189], v[48:51]
	v_mfma_f32_16x16x32_bf16 v[36:39], v[170:173], v[194:197], v[36:39]
	v_mfma_f32_16x16x32_bf16 v[32:35], v[178:181], v[194:197], v[32:35]
	v_mfma_f32_16x16x32_bf16 v[20:23], v[170:173], v[202:205], v[20:23]
	v_mfma_f32_16x16x32_bf16 v[16:19], v[178:181], v[202:205], v[16:19]
	v_mfma_f32_16x16x32_bf16 v[4:7], v[170:173], v[210:213], v[4:7]
	v_mfma_f32_16x16x32_bf16 v[0:3], v[178:181], v[210:213], v[0:3]
	s_setprio 0
	s_barrier
	s_add_i32 s79, 0, 0x18000
	s_add_i32 s80, 0, 0x1c000
	v_add_u32_e32 v162, s79, v153
	v_add_u32_e32 v178, s80, v153
	ds_read_b128 v[144:147], v162
	ds_read_b128 v[148:151], v162 offset:1024
	ds_read_b128 v[158:161], v162 offset:2048
	ds_read_b128 v[162:165], v162 offset:3072
	ds_read_b128 v[166:169], v178
	ds_read_b128 v[170:173], v178 offset:1024
	ds_read_b128 v[174:177], v178 offset:2048
	ds_read_b128 v[178:181], v178 offset:3072
	s_add_u32 s68, s68, 0x40000
	s_addc_u32 s69, s69, 0
	s_mov_b32 m0, s34
	v_lshl_add_u64 v[226:227], s[68:69], 0, v[128:129]
	ds_read_b128 v[182:185], v157 offset:32768
	ds_read_b128 v[186:189], v157 offset:33792
	ds_read_b128 v[190:193], v157 offset:34816
	ds_read_b128 v[194:197], v157 offset:35840
	ds_read_b128 v[198:201], v157 offset:36864
	ds_read_b128 v[202:205], v157 offset:37888
	ds_read_b128 v[206:209], v157 offset:38912
	ds_read_b128 v[210:213], v157 offset:39936
	global_load_lds_dwordx4 v[226:227], off
	v_lshl_add_u64 v[226:227], s[68:69], 0, v[132:133]
	s_mov_b32 m0, s35
	s_nop 0
	global_load_lds_dwordx4 v[226:227], off
	s_waitcnt vmcnt(8)
	s_waitcnt lgkmcnt(0)
	s_barrier
	s_setprio 1
	s_waitcnt lgkmcnt(0)
	v_mfma_f32_16x16x32_bf16 v[124:127], v[144:147], v[182:185], v[124:127]
	v_mfma_f32_16x16x32_bf16 v[120:123], v[158:161], v[182:185], v[120:123]
	v_mfma_f32_16x16x32_bf16 v[108:111], v[144:147], v[190:193], v[108:111]
	v_mfma_f32_16x16x32_bf16 v[104:107], v[158:161], v[190:193], v[104:107]
	v_mfma_f32_16x16x32_bf16 v[92:95], v[144:147], v[198:201], v[92:95]
	v_mfma_f32_16x16x32_bf16 v[88:91], v[158:161], v[198:201], v[88:91]
	v_mfma_f32_16x16x32_bf16 v[76:79], v[144:147], v[206:209], v[76:79]
	v_mfma_f32_16x16x32_bf16 v[72:75], v[158:161], v[206:209], v[72:75]
	v_mfma_f32_16x16x32_bf16 v[124:127], v[148:151], v[186:189], v[124:127]
	v_mfma_f32_16x16x32_bf16 v[120:123], v[162:165], v[186:189], v[120:123]
	v_mfma_f32_16x16x32_bf16 v[108:111], v[148:151], v[194:197], v[108:111]
	v_mfma_f32_16x16x32_bf16 v[104:107], v[162:165], v[194:197], v[104:107]
	v_mfma_f32_16x16x32_bf16 v[92:95], v[148:151], v[202:205], v[92:95]
	v_mfma_f32_16x16x32_bf16 v[88:91], v[162:165], v[202:205], v[88:91]
	v_mfma_f32_16x16x32_bf16 v[76:79], v[148:151], v[210:213], v[76:79]
	v_mfma_f32_16x16x32_bf16 v[72:75], v[162:165], v[210:213], v[72:75]
	s_setprio 0
	s_setprio 1
	v_mfma_f32_16x16x32_bf16 v[116:119], v[166:169], v[182:185], v[116:119]
	v_mfma_f32_16x16x32_bf16 v[112:115], v[174:177], v[182:185], v[112:115]
	v_mfma_f32_16x16x32_bf16 v[100:103], v[166:169], v[190:193], v[100:103]
	v_mfma_f32_16x16x32_bf16 v[96:99], v[174:177], v[190:193], v[96:99]
	v_mfma_f32_16x16x32_bf16 v[84:87], v[166:169], v[198:201], v[84:87]
	v_mfma_f32_16x16x32_bf16 v[80:83], v[174:177], v[198:201], v[80:83]
	v_mfma_f32_16x16x32_bf16 v[68:71], v[166:169], v[206:209], v[68:71]
	v_mfma_f32_16x16x32_bf16 v[64:67], v[174:177], v[206:209], v[64:67]
	v_mfma_f32_16x16x32_bf16 v[116:119], v[170:173], v[186:189], v[116:119]
	v_mfma_f32_16x16x32_bf16 v[112:115], v[178:181], v[186:189], v[112:115]
	v_mfma_f32_16x16x32_bf16 v[100:103], v[170:173], v[194:197], v[100:103]
	v_mfma_f32_16x16x32_bf16 v[96:99], v[178:181], v[194:197], v[96:99]
	v_mfma_f32_16x16x32_bf16 v[84:87], v[170:173], v[202:205], v[84:87]
	v_mfma_f32_16x16x32_bf16 v[80:83], v[178:181], v[202:205], v[80:83]
	v_mfma_f32_16x16x32_bf16 v[68:71], v[170:173], v[210:213], v[68:71]
	v_mfma_f32_16x16x32_bf16 v[64:67], v[178:181], v[210:213], v[64:67]
	s_setprio 0
	s_barrier
; #define PG8_STAGE(bufoff, gbase, voff) do { _Pragma("unroll") for (int _i = 0; _i < 2; ++_i) \
;         __builtin_amdgcn_global_load_lds((const unsigned*)((const char*)(gbase) + (voff)[_i]), (PG8_LAS unsigned*)(lds + (bufoff) + ldsw + _i * 8192), 16, 0, 0); } while (0)
; #define PG8_LDA(dst, b, h) do { _Pragma("unroll") for (int m = 0; m < 4; ++m) _Pragma("unroll") for (int k = 0; k < 2; ++k) dst[m][k] = *(const PG8_LAS bf16x8*)(lds + PG8_SA(b, h) + aoff + m * 2048 + k * 1024); } while (0)
; #define PG8_MMA(ai, bj, At, Bt) do { __builtin_amdgcn_s_setprio(1); _Pragma("unroll") for (int m = 0; m < 4; ++m) _Pragma("unroll") for (int n = 0; n < 2; ++n) _Pragma("unroll") for (int k = 0; k < 2; ++k) \
;         acc[ai][bj][m][n] = __builtin_amdgcn_mfma_f32_16x16x32_bf16(Bt[n][k], At[m][k], acc[ai][bj][m][n], 0, 0, 0); __builtin_amdgcn_s_setprio(0); } while (0)
; #define PG8_WAIT_V(n) asm volatile("s_waitcnt vmcnt(" #n ")" ::: "memory")
; #define PG8_WAIT_L(n) asm volatile("s_waitcnt lgkmcnt(" #n ")" ::: "memory")
; #define PG8_BAR __builtin_amdgcn_s_barrier()
; #define PG8_SCHED __builtin_amdgcn_sched_barrier(0)
;     __device__ __forceinline__ void operator()(const f32x4 (&acc)[2][2][4][2], const Unit& u, int wr, int wc, int fr, int fq) const {
;         const int row0 = u.pm * BM + wr * 64 + fr, col0 = u.pn * BM + wc * 32 + 8 * fq;
; #pragma unroll
;         for (int ai = 0; ai < 2; ++ai)
; #pragma unroll
;             for (int m = 0; m < 4; ++m) { const size_t row = (size_t)(row0 + ai * HALF + m * 16); float s = 0.f;
; #pragma unroll
;                 for (int bj = 0; bj < 2; ++bj) { const size_t off = row * 1024 + col0 + bj * HALF; const u32x4 h = __builtin_nontemporal_load((const u32x4*)(XB + off));
; template <class Epi, class Sched, bool ALIGN_EPI = false, bool SP2 = false>
; __device__ __forceinline__ void gemm_phase(PG8_LAS unsigned char* lds, const Gemm g, const Sched& S, const Epi& E, const int wave_s) {
;     ...
;             PG8_WAIT_V(8); PG8_WAIT_L(0); PG8_BAR; PG8_MMA(0, 0, At, B0); PG8_MMA(0, 1, At, B1); PG8_BAR; PG8_SCHED;
;             PG8_LDA(At, 1, 1); PG8_STAGE(PG8_SB(1, 0), b3, voffB); PG8_STAGE(PG8_SB(1, 1), b3 + hB, voffB); PG8_STAGE(PG8_SA(1, 0), a3, voffA);
;             PG8_WAIT_V(8); PG8_WAIT_L(0); PG8_BAR; PG8_MMA(1, 0, At, B0); PG8_MMA(1, 1, At, B1); PG8_BAR; PG8_SCHED;
	s_add_i32 s68, s79, s11
	v_lshl_add_u64 v[218:219], v[218:219], 0, s[36:37]
	s_mov_b32 m0, s68
	ds_read_b128 v[182:185], v157 offset:49152
	ds_read_b128 v[186:189], v157 offset:50176
	ds_read_b128 v[190:193], v157 offset:51200
	ds_read_b128 v[194:197], v157 offset:52224
	ds_read_b128 v[198:201], v157 offset:53248
	ds_read_b128 v[202:205], v157 offset:54272
	ds_read_b128 v[206:209], v157 offset:55296
	ds_read_b128 v[210:213], v157 offset:56320
	global_load_lds_dwordx4 v[218:219], off
	s_add_i32 m0, s68, 0x2000
	s_add_u32 s66, s66, 0x40080
	v_lshl_add_u64 v[218:219], v[220:221], 0, s[36:37]
	s_addc_u32 s67, s67, 0
	s_add_i32 s68, s80, s11
	global_load_lds_dwordx4 v[218:219], off
	v_lshl_add_u64 v[218:219], s[66:67], 0, v[130:131]
	s_mov_b32 m0, s68
	s_nop 0
	global_load_lds_dwordx4 v[218:219], off
	v_lshl_add_u64 v[218:219], s[66:67], 0, v[134:135]
	s_add_i32 m0, s68, 0x2000
	s_nop 0
	global_load_lds_dwordx4 v[218:219], off
	v_lshl_add_u64 v[218:219], v[222:223], 0, s[36:37]
	s_mov_b32 m0, s70
	s_nop 0
	global_load_lds_dwordx4 v[218:219], off
	v_lshl_add_u64 v[218:219], v[224:225], 0, s[36:37]
	s_mov_b32 m0, s71
	s_nop 0
	global_load_lds_dwordx4 v[218:219], off
	s_waitcnt vmcnt(8)
	s_waitcnt lgkmcnt(0)
	s_barrier
	s_setprio 1
	s_waitcnt lgkmcnt(0)
	v_mfma_f32_16x16x32_bf16 v[60:63], v[144:147], v[182:185], v[60:63]
	v_mfma_f32_16x16x32_bf16 v[56:59], v[158:161], v[182:185], v[56:59]
	v_mfma_f32_16x16x32_bf16 v[44:47], v[144:147], v[190:193], v[44:47]
	v_mfma_f32_16x16x32_bf16 v[40:43], v[158:161], v[190:193], v[40:43]
	v_mfma_f32_16x16x32_bf16 v[28:31], v[144:147], v[198:201], v[28:31]
	v_mfma_f32_16x16x32_bf16 v[24:27], v[158:161], v[198:201], v[24:27]
	v_mfma_f32_16x16x32_bf16 v[12:15], v[144:147], v[206:209], v[12:15]
	v_mfma_f32_16x16x32_bf16 v[8:11], v[158:161], v[206:209], v[8:11]
	v_mfma_f32_16x16x32_bf16 v[60:63], v[148:151], v[186:189], v[60:63]
	v_mfma_f32_16x16x32_bf16 v[56:59], v[162:165], v[186:189], v[56:59]
	v_mfma_f32_16x16x32_bf16 v[44:47], v[148:151], v[194:197], v[44:47]
	v_mfma_f32_16x16x32_bf16 v[40:43], v[162:165], v[194:197], v[40:43]
	v_mfma_f32_16x16x32_bf16 v[28:31], v[148:151], v[202:205], v[28:31]
	v_mfma_f32_16x16x32_bf16 v[24:27], v[162:165], v[202:205], v[24:27]
	v_mfma_f32_16x16x32_bf16 v[12:15], v[148:151], v[210:213], v[12:15]
	v_mfma_f32_16x16x32_bf16 v[8:11], v[162:165], v[210:213], v[8:11]
	s_setprio 0
	s_setprio 1
	v_mfma_f32_16x16x32_bf16 v[52:55], v[166:169], v[182:185], v[52:55]
	v_mfma_f32_16x16x32_bf16 v[48:51], v[174:177], v[182:185], v[48:51]
	v_mfma_f32_16x16x32_bf16 v[36:39], v[166:169], v[190:193], v[36:39]
	v_mfma_f32_16x16x32_bf16 v[32:35], v[174:177], v[190:193], v[32:35]
	v_mfma_f32_16x16x32_bf16 v[20:23], v[166:169], v[198:201], v[20:23]
	v_mfma_f32_16x16x32_bf16 v[16:19], v[174:177], v[198:201], v[16:19]
	v_mfma_f32_16x16x32_bf16 v[4:7], v[166:169], v[206:209], v[4:7]
	v_mfma_f32_16x16x32_bf16 v[0:3], v[174:177], v[206:209], v[0:3]
	v_mfma_f32_16x16x32_bf16 v[52:55], v[170:173], v[186:189], v[52:55]
	v_mfma_f32_16x16x32_bf16 v[48:51], v[178:181], v[186:189], v[48:51]
	v_mfma_f32_16x16x32_bf16 v[36:39], v[170:173], v[194:197], v[36:39]
	v_mfma_f32_16x16x32_bf16 v[32:35], v[178:181], v[194:197], v[32:35]
	v_mfma_f32_16x16x32_bf16 v[20:23], v[170:173], v[202:205], v[20:23]
	v_mfma_f32_16x16x32_bf16 v[16:19], v[178:181], v[202:205], v[16:19]
	v_mfma_f32_16x16x32_bf16 v[4:7], v[170:173], v[210:213], v[4:7]
	v_mfma_f32_16x16x32_bf16 v[0:3], v[178:181], v[210:213], v[0:3]
	s_setprio 0
	s_cmpk_lg_i32 s78, 12
	s_cbranch_scc1 .Learly_LBB0_699
	v_lshl_add_u32 v150, s62, 8, v152
	v_lshl_or_b32 v148, s60, 8, v154
	v_ashrrev_i32_e32 v151, 31, v150
	v_ashrrev_i32_e32 v149, 31, v148
	v_lshlrev_b64 v[144:145], 10, v[150:151]
	v_lshl_add_u64 v[144:145], v[144:145], 0, v[148:149]
	v_lshlrev_b64 v[146:147], 1, v[144:145]
	v_lshl_add_u64 v[162:163], s[24:25], 0, v[146:147]
	global_load_dwordx4 v[168:171], v[162:163], off nt
	global_load_dwordx4 v[172:175], v[162:163], off offset:256 nt
	s_mov_b32 s99, 0
	s_mov_b32 s98, 0x8000
	v_lshl_add_u64 v[212:213], v[162:163], 0, s[98:99]
	global_load_dwordx4 v[176:179], v[212:213], off nt
	global_load_dwordx4 v[180:183], v[212:213], off offset:256 nt
	s_mov_b32 s98, 0x10000
	v_lshl_add_u64 v[212:213], v[162:163], 0, s[98:99]
	global_load_dwordx4 v[184:187], v[212:213], off nt
	global_load_dwordx4 v[188:191], v[212:213], off offset:256 nt
	s_mov_b32 s98, 0x18000
	v_lshl_add_u64 v[212:213], v[162:163], 0, s[98:99]
	global_load_dwordx4 v[192:195], v[212:213], off nt
	global_load_dwordx4 v[196:199], v[212:213], off offset:256 nt
	s_mov_b32 s98, 0x40000
	v_lshl_add_u64 v[212:213], v[162:163], 0, s[98:99]
	global_load_dwordx4 v[200:203], v[212:213], off nt
	global_load_dwordx4 v[204:207], v[212:213], off offset:256 nt
	s_mov_b32 s98, 0x48000
	v_lshl_add_u64 v[212:213], v[162:163], 0, s[98:99]
	global_load_dwordx4 v[208:211], v[212:213], off nt
	global_load_dwordx4 v[228:231], v[212:213], off offset:256 nt
	s_mov_b32 s98, 0x50000
	v_lshl_add_u64 v[212:213], v[162:163], 0, s[98:99]
	global_load_dwordx4 v[232:235], v[212:213], off nt
	global_load_dwordx4 v[236:239], v[212:213], off offset:256 nt
	s_mov_b32 s98, 0x58000
	v_lshl_add_u64 v[212:213], v[162:163], 0, s[98:99]
	global_load_dwordx4 v[240:243], v[212:213], off nt
	global_load_dwordx4 v[244:247], v[212:213], off offset:256 nt
	v_lshl_add_u64 v[144:145], s[14:15], 0, v[146:147]
; __device__ __forceinline__ float bflo(unsigned w) { return __uint_as_float(w << 16); }
; __device__ __forceinline__ float bfhi(unsigned w) { return __uint_as_float(w & 0xffff0000u); }
; __device__ __forceinline__ u32x4 pk8(const f32x4 a, const f32x4 b) { u32x4 w; w.x = pkbf(a[0], a[1]); w.y = pkbf(a[2], a[3]); w.z = pkbf(b[0], b[1]); w.w = pkbf(b[2], b[3]); return w; }
; __device__ __forceinline__ float sumsq4(const f32x4 a) { return (a[0] * a[0] + a[1] * a[1]) + (a[2] * a[2] + a[3] * a[3]); }
; #define PG8_BAR __builtin_amdgcn_s_barrier()
;     __device__ __forceinline__ void operator()(const f32x4 (&acc)[2][2][4][2], const Unit& u, int wr, int wc, int fr, int fq) const {
;         const int row0 = u.pm * BM + wr * 64 + fr, col0 = u.pn * BM + wc * 32 + 8 * fq;
; #pragma unroll
;         for (int ai = 0; ai < 2; ++ai)
; #pragma unroll
;             for (int m = 0; m < 4; ++m) { const size_t row = (size_t)(row0 + ai * HALF + m * 16); float s = 0.f;
; #pragma unroll
;                 for (int bj = 0; bj < 2; ++bj) { const size_t off = row * 1024 + col0 + bj * HALF; const u32x4 h = __builtin_nontemporal_load((const u32x4*)(XB + off));
;                     f32x4 a = acc[ai][bj][m][0], b = acc[ai][bj][m][1];
;                     a[0] += bflo(h.x); a[1] += bfhi(h.x); a[2] += bflo(h.y); a[3] += bfhi(h.y); b[0] += bflo(h.z); b[1] += bfhi(h.z); b[2] += bflo(h.w); b[3] += bfhi(h.w);
;                     s += sumsq4(a) + sumsq4(b); *(u32x4*)(HB + off) = pk8(a, b); }
;                 s += __shfl_xor(s, 16); s += __shfl_xor(s, 32);
;                 if (fq == 0) unsafeAtomicAdd(ss + row, s); }
; template <class Epi, class Sched, bool ALIGN_EPI = false, bool SP2 = false>
; __device__ __forceinline__ void gemm_phase(PG8_LAS unsigned char* lds, const Gemm g, const Sched& S, const Epi& E, const int wave_s) {
;     ...
;         if constexpr (ALIGN_EPI) { if (wr == 0) PG8_BAR; }
.Learly_LBB0_699:
	s_barrier
	s_add_i32 s78, s78, 2
	s_add_u32 s64, s64, 0x100
	s_addc_u32 s65, s65, 0
	s_add_u32 s61, s61, 0x100
	s_addc_u32 s77, s77, 0
	s_cmp_gt_u32 s78, 13
	s_cbranch_scc0 .LBB0_696
	s_and_b64 vcc, exec, s[38:39]
	s_cbranch_vccz .LBB0_699
	s_barrier
.LBB0_699:
	s_waitcnt vmcnt(15)
	v_mov_b32_e32 v158, v168
	v_mov_b32_e32 v159, v169
	v_mov_b32_e32 v160, v170
	v_mov_b32_e32 v161, v171
	v_lshlrev_b32_e32 v164, 16, v158
	v_and_b32_e32 v165, 0xffff0000, v158
	v_lshlrev_b32_e32 v158, 16, v159
	v_and_b32_e32 v159, 0xffff0000, v159
	v_lshlrev_b32_e32 v166, 16, v160
	v_and_b32_e32 v167, 0xffff0000, v160
	v_lshlrev_b32_e32 v160, 16, v161
	v_and_b32_e32 v161, 0xffff0000, v161
	v_pk_add_f32 v[124:125], v[124:125], v[164:165]
	v_pk_add_f32 v[126:127], v[126:127], v[158:159]
	v_pk_add_f32 v[158:159], v[120:121], v[166:167]
	v_pk_add_f32 v[160:161], v[122:123], v[160:161]
	v_cvt_pk_bf16_f32 v120, v124, v125
	v_cvt_pk_bf16_f32 v121, v126, v127
	v_cvt_pk_bf16_f32 v122, v158, v159
	v_cvt_pk_bf16_f32 v123, v160, v161
	global_store_dwordx4 v[144:145], v[120:123], off
	v_pk_mul_f32 v[124:125], v[124:125], v[124:125]
	v_pk_mul_f32 v[126:127], v[126:127], v[126:127]
	v_pk_mul_f32 v[158:159], v[158:159], v[158:159]
	v_pk_mul_f32 v[160:161], v[160:161], v[160:161]
	v_add_f32_e32 v158, v158, v159
	v_add_f32_e32 v160, v160, v161
	v_add_f32_e32 v126, v126, v127
	v_add_f32_e32 v124, v124, v125
	v_add_f32_e32 v125, v158, v160
	v_add_f32_e32 v124, v124, v126
	v_add_f32_e32 v158, v124, v125
	s_waitcnt vmcnt(15)
	v_mov_b32_e32 v120, v172
	v_mov_b32_e32 v121, v173
	v_mov_b32_e32 v122, v174
	v_mov_b32_e32 v123, v175
	v_lshlrev_b32_e32 v124, 16, v120
	v_and_b32_e32 v125, 0xffff0000, v120
	v_lshlrev_b32_e32 v120, 16, v121
	v_and_b32_e32 v121, 0xffff0000, v121
	v_lshlrev_b32_e32 v126, 16, v122
	v_and_b32_e32 v127, 0xffff0000, v122
	v_lshlrev_b32_e32 v122, 16, v123
	v_and_b32_e32 v123, 0xffff0000, v123
	v_pk_add_f32 v[116:117], v[116:117], v[124:125]
	v_pk_add_f32 v[118:119], v[118:119], v[120:121]
	v_pk_add_f32 v[112:113], v[112:113], v[126:127]
	v_pk_add_f32 v[114:115], v[114:115], v[122:123]
	v_pk_mul_f32 v[120:121], v[116:117], v[116:117]
	v_pk_mul_f32 v[122:123], v[118:119], v[118:119]
	v_pk_mul_f32 v[124:125], v[112:113], v[112:113]
	v_pk_mul_f32 v[126:127], v[114:115], v[114:115]
	v_add_f32_e32 v124, v124, v125
	v_add_f32_e32 v126, v126, v127
	v_add_f32_e32 v122, v122, v123
	v_add_f32_e32 v120, v120, v121
	v_add_f32_e32 v121, v124, v126
	v_add_f32_e32 v120, v120, v122
	v_add_f32_e32 v120, v120, v121
	v_add_f32_e32 v120, v158, v120
	ds_bpermute_b32 v121, v215, v120
	v_cvt_pk_bf16_f32 v116, v116, v117
	v_cvt_pk_bf16_f32 v117, v118, v119
	v_cvt_pk_bf16_f32 v119, v114, v115
	v_cvt_pk_bf16_f32 v118, v112, v113
	s_waitcnt lgkmcnt(0)
	v_add_f32_e32 v114, v120, v121
	ds_bpermute_b32 v115, v216, v114
	v_or_b32_e32 v112, 0x100, v146
	v_mov_b32_e32 v113, v147
	v_lshl_add_u64 v[112:113], s[14:15], 0, v[112:113]
	global_store_dwordx4 v[112:113], v[116:119], off
	v_lshl_add_u64 v[112:113], v[150:151], 2, s[26:27]
	s_and_saveexec_b64 s[60:61], s[4:5]
	s_cbranch_execz .LBB0_701
	s_waitcnt lgkmcnt(0)
	v_add_f32_e32 v114, v114, v115
	global_atomic_add_f32 v[112:113], v114, off

;     __device__ __forceinline__ void mid(f32x4 (&acc)[2][2][4][2], const Unit& u, int wr, int wc, int fr, int fq) const { scale(acc, u, wr, wc, fr, fq, 0); }
; #define PG8_STAGE(bufoff, gbase, voff) do { _Pragma("unroll") for (int _i = 0; _i < 2; ++_i) \
;         __builtin_amdgcn_global_load_lds((const unsigned*)((const char*)(gbase) + (voff)[_i]), (PG8_LAS unsigned*)(lds + (bufoff) + ldsw + _i * 8192), 16, 0, 0); } while (0)
; #define PG8_LDA(dst, b, h) do { _Pragma("unroll") for (int m = 0; m < 4; ++m) _Pragma("unroll") for (int k = 0; k < 2; ++k) dst[m][k] = *(const PG8_LAS bf16x8*)(lds + PG8_SA(b, h) + aoff + m * 2048 + k * 1024); } while (0)
; #define PG8_LDB(dst, b, h) do { _Pragma("unroll") for (int n = 0; n < 2; ++n) _Pragma("unroll") for (int k = 0; k < 2; ++k) dst[n][k] = *(const PG8_LAS bf16x8*)(lds + PG8_SB(b, h) + boff + n * 2048 + k * 1024); } while (0)
; #define PG8_WAIT_V(n) asm volatile("s_waitcnt vmcnt(" #n ")" ::: "memory")
; #define PG8_WAIT_L(n) asm volatile("s_waitcnt lgkmcnt(" #n ")" ::: "memory")
; template <class Epi, class Sched, bool ALIGN_EPI = false, bool SP2 = false>
; __device__ __forceinline__ void gemm_phase(PG8_LAS unsigned char* lds, const Gemm g, const Sched& S, const Epi& E, const int wave_s) {
;     ...
;         for (int t = 0; t < nt; t += 2) {
;             if constexpr (Epi::MIDK > 0) { if (t == Epi::MIDK) E.mid(acc, cur, wr, wc, fr, fq); }
;             const bool last = (t == nt - 2);
;             if constexpr (Epi::HAS_PRE) { if (last) E.pre(cur, wr, fr, pf); }
;             const char* a1 = cA + (size_t)(t + 1) * kstep;
;             const char* a2 = last ? nA : cA + (size_t)(t + 2) * kstep; const char* b2 = last ? nB : cB + (size_t)(t + 2) * kstep;
;             const char* a3 = a2 + kstep; const char* b3 = b2 + kstep;
;             if (last && has_next) S.a_ready(nxt);
;             if constexpr (SP2) {
;             PG8_LDB(B0, 0, 0); PG8_LDB(B1, 0, 1); PG8_SCHED; PG8_LDA(At, 0, 0); PG8_STAGE(PG8_SA(1, 1), a1 + hA, voffA);
;             PG8_WAIT_V(8); PG8_WAIT_L(0); PG8_BAR; PG8_MMA(0, 0, At, B0); PG8_MMA(0, 1, At, B1); PG8_BAR; PG8_SCHED;
;             PG8_LDA(At, 0, 1); PG8_STAGE(PG8_SB(0, 0), b2, voffB); PG8_STAGE(PG8_SB(0, 1), b2 + hB, voffB); PG8_STAGE(PG8_SA(0, 0), a2, voffA);
;             PG8_WAIT_V(8); PG8_WAIT_L(0); PG8_BAR; PG8_MMA(1, 0, At, B0); PG8_MMA(1, 1, At, B1); PG8_BAR; PG8_SCHED;
.LBB0_856:
	ds_read_b128 v[144:147], v151
	ds_read_b128 v[154:157], v151 offset:1024
	ds_read_b128 v[158:161], v151 offset:2048
	ds_read_b128 v[162:165], v151 offset:3072
	ds_read_b128 v[166:169], v152
	ds_read_b128 v[170:173], v152 offset:1024
	ds_read_b128 v[174:177], v152 offset:2048
	ds_read_b128 v[178:181], v152 offset:3072
	s_add_u32 s50, s48, 0xfff00080
	s_addc_u32 s51, s49, -1
	s_cmp_eq_u32 s64, 60
	s_cselect_b32 s55, s8, s51
	s_cselect_b32 s54, s9, s50
	s_cselect_b32 s51, s37, s63
	s_cselect_b32 s50, s39, s45
	v_lshl_add_u64 v[218:219], s[48:49], 0, v[136:137]
	s_add_i32 m0, s12, 0xc000
	ds_read_b128 v[182:185], v153
	ds_read_b128 v[186:189], v153 offset:1024
	ds_read_b128 v[190:193], v153 offset:2048
	ds_read_b128 v[194:197], v153 offset:3072
	ds_read_b128 v[198:201], v153 offset:4096
	ds_read_b128 v[202:205], v153 offset:5120
	ds_read_b128 v[206:209], v153 offset:6144
	ds_read_b128 v[210:213], v153 offset:7168
	global_load_lds_dwordx4 v[218:219], off
	v_lshl_add_u64 v[218:219], s[48:49], 0, v[138:139]
	s_add_i32 m0, s12, 0xe000
	s_nop 0
	global_load_lds_dwordx4 v[218:219], off
	s_waitcnt vmcnt(8)
	s_waitcnt lgkmcnt(0)
	s_barrier
	s_setprio 1
	s_waitcnt lgkmcnt(0)
	v_mfma_f32_16x16x32_bf16 v[124:127], v[144:147], v[182:185], v[124:127]
	v_mfma_f32_16x16x32_bf16 v[120:123], v[158:161], v[182:185], v[120:123]
	v_mfma_f32_16x16x32_bf16 v[108:111], v[144:147], v[190:193], v[108:111]
	v_mfma_f32_16x16x32_bf16 v[104:107], v[158:161], v[190:193], v[104:107]
	v_mfma_f32_16x16x32_bf16 v[92:95], v[144:147], v[198:201], v[92:95]
	v_mfma_f32_16x16x32_bf16 v[88:91], v[158:161], v[198:201], v[88:91]
	v_mfma_f32_16x16x32_bf16 v[76:79], v[144:147], v[206:209], v[76:79]
	v_mfma_f32_16x16x32_bf16 v[72:75], v[158:161], v[206:209], v[72:75]
	v_mfma_f32_16x16x32_bf16 v[124:127], v[154:157], v[186:189], v[124:127]
	v_mfma_f32_16x16x32_bf16 v[120:123], v[162:165], v[186:189], v[120:123]
	v_mfma_f32_16x16x32_bf16 v[108:111], v[154:157], v[194:197], v[108:111]
	v_mfma_f32_16x16x32_bf16 v[104:107], v[162:165], v[194:197], v[104:107]
	v_mfma_f32_16x16x32_bf16 v[92:95], v[154:157], v[202:205], v[92:95]
	v_mfma_f32_16x16x32_bf16 v[88:91], v[162:165], v[202:205], v[88:91]
	v_mfma_f32_16x16x32_bf16 v[76:79], v[154:157], v[210:213], v[76:79]
	v_mfma_f32_16x16x32_bf16 v[72:75], v[162:165], v[210:213], v[72:75]
	s_setprio 0
	s_setprio 1
	v_mfma_f32_16x16x32_bf16 v[116:119], v[166:169], v[182:185], v[116:119]
	v_mfma_f32_16x16x32_bf16 v[112:115], v[174:177], v[182:185], v[112:115]
	v_mfma_f32_16x16x32_bf16 v[100:103], v[166:169], v[190:193], v[100:103]
	v_mfma_f32_16x16x32_bf16 v[96:99], v[174:177], v[190:193], v[96:99]
	v_mfma_f32_16x16x32_bf16 v[84:87], v[166:169], v[198:201], v[84:87]
	v_mfma_f32_16x16x32_bf16 v[80:83], v[174:177], v[198:201], v[80:83]
	v_mfma_f32_16x16x32_bf16 v[68:71], v[166:169], v[206:209], v[68:71]
	v_mfma_f32_16x16x32_bf16 v[64:67], v[174:177], v[206:209], v[64:67]
	v_mfma_f32_16x16x32_bf16 v[116:119], v[170:173], v[186:189], v[116:119]
	v_mfma_f32_16x16x32_bf16 v[112:115], v[178:181], v[186:189], v[112:115]
	v_mfma_f32_16x16x32_bf16 v[100:103], v[170:173], v[194:197], v[100:103]
	v_mfma_f32_16x16x32_bf16 v[96:99], v[178:181], v[194:197], v[96:99]
	v_mfma_f32_16x16x32_bf16 v[84:87], v[170:173], v[202:205], v[84:87]
	v_mfma_f32_16x16x32_bf16 v[80:83], v[178:181], v[202:205], v[80:83]
	v_mfma_f32_16x16x32_bf16 v[68:71], v[170:173], v[210:213], v[68:71]
	v_mfma_f32_16x16x32_bf16 v[64:67], v[178:181], v[210:213], v[64:67]
	s_setprio 0
	s_barrier
	s_add_i32 s65, s61, s11
	v_lshl_add_u64 v[218:219], s[50:51], 0, v[130:131]
	s_mov_b32 m0, s65
	ds_read_b128 v[182:185], v153 offset:16384
	ds_read_b128 v[186:189], v153 offset:17408
	ds_read_b128 v[190:193], v153 offset:18432
	ds_read_b128 v[194:197], v153 offset:19456
	ds_read_b128 v[198:201], v153 offset:20480
	ds_read_b128 v[202:205], v153 offset:21504
	ds_read_b128 v[206:209], v153 offset:22528
	ds_read_b128 v[210:213], v153 offset:23552
	global_load_lds_dwordx4 v[218:219], off
	s_add_i32 m0, s65, 0x2000
	s_add_u32 s66, s50, 0x100000
	v_lshl_add_u64 v[220:221], s[50:51], 0, v[134:135]
	s_addc_u32 s67, s51, 0
	s_add_i32 s65, s62, s11
	global_load_lds_dwordx4 v[220:221], off
	v_lshl_add_u64 v[222:223], s[66:67], 0, v[130:131]
	s_mov_b32 m0, s65
	v_lshl_add_u64 v[224:225], s[54:55], 0, v[132:133]
	global_load_lds_dwordx4 v[222:223], off
	v_lshl_add_u64 v[222:223], s[66:67], 0, v[134:135]
	s_add_i32 m0, s65, 0x2000
	s_nop 0
	global_load_lds_dwordx4 v[222:223], off
	v_lshl_add_u64 v[222:223], s[54:55], 0, v[128:129]
	s_mov_b32 m0, s12
	s_nop 0
	global_load_lds_dwordx4 v[222:223], off
	s_mov_b32 m0, s13
	s_nop 0
	global_load_lds_dwordx4 v[224:225], off
	s_waitcnt vmcnt(8)
	s_waitcnt lgkmcnt(0)
	s_barrier
; #define PG8_STAGE(bufoff, gbase, voff) do { _Pragma("unroll") for (int _i = 0; _i < 2; ++_i) \
;         __builtin_amdgcn_global_load_lds((const unsigned*)((const char*)(gbase) + (voff)[_i]), (PG8_LAS unsigned*)(lds + (bufoff) + ldsw + _i * 8192), 16, 0, 0); } while (0)
; #define PG8_LDA(dst, b, h) do { _Pragma("unroll") for (int m = 0; m < 4; ++m) _Pragma("unroll") for (int k = 0; k < 2; ++k) dst[m][k] = *(const PG8_LAS bf16x8*)(lds + PG8_SA(b, h) + aoff + m * 2048 + k * 1024); } while (0)
; #define PG8_LDB(dst, b, h) do { _Pragma("unroll") for (int n = 0; n < 2; ++n) _Pragma("unroll") for (int k = 0; k < 2; ++k) dst[n][k] = *(const PG8_LAS bf16x8*)(lds + PG8_SB(b, h) + boff + n * 2048 + k * 1024); } while (0)
; #define PG8_MMA(ai, bj, At, Bt) do { __builtin_amdgcn_s_setprio(1); _Pragma("unroll") for (int m = 0; m < 4; ++m) _Pragma("unroll") for (int n = 0; n < 2; ++n) _Pragma("unroll") for (int k = 0; k < 2; ++k) \
;         acc[ai][bj][m][n] = __builtin_amdgcn_mfma_f32_16x16x32_bf16(Bt[n][k], At[m][k], acc[ai][bj][m][n], 0, 0, 0); __builtin_amdgcn_s_setprio(0); } while (0)
; #define PG8_WAIT_V(n) asm volatile("s_waitcnt vmcnt(" #n ")" ::: "memory")
; #define PG8_WAIT_L(n) asm volatile("s_waitcnt lgkmcnt(" #n ")" ::: "memory")
; #define PG8_BAR __builtin_amdgcn_s_barrier()
; #define PG8_SCHED __builtin_amdgcn_sched_barrier(0)
; template <class Epi, class Sched, bool ALIGN_EPI = false, bool SP2 = false>
; __device__ __forceinline__ void gemm_phase(PG8_LAS unsigned char* lds, const Gemm g, const Sched& S, const Epi& E, const int wave_s) {
;     ...
;             PG8_WAIT_V(8); PG8_WAIT_L(0); PG8_BAR; PG8_MMA(1, 0, At, B0); PG8_MMA(1, 1, At, B1); PG8_BAR; PG8_SCHED;
;             PG8_LDB(B0, 1, 0); PG8_LDB(B1, 1, 1); PG8_SCHED; PG8_LDA(At, 1, 0); PG8_STAGE(PG8_SA(0, 1), a2 + hA, voffA);
;             PG8_WAIT_V(8); PG8_WAIT_L(0); PG8_BAR; PG8_MMA(0, 0, At, B0); PG8_MMA(0, 1, At, B1); PG8_BAR; PG8_SCHED;
	s_setprio 1
	s_waitcnt lgkmcnt(0)
	v_mfma_f32_16x16x32_bf16 v[60:63], v[144:147], v[182:185], v[60:63]
	v_mfma_f32_16x16x32_bf16 v[56:59], v[158:161], v[182:185], v[56:59]
	v_mfma_f32_16x16x32_bf16 v[44:47], v[144:147], v[190:193], v[44:47]
	v_mfma_f32_16x16x32_bf16 v[40:43], v[158:161], v[190:193], v[40:43]
	v_mfma_f32_16x16x32_bf16 v[28:31], v[144:147], v[198:201], v[28:31]
	v_mfma_f32_16x16x32_bf16 v[24:27], v[158:161], v[198:201], v[24:27]
	v_mfma_f32_16x16x32_bf16 v[12:15], v[144:147], v[206:209], v[12:15]
	v_mfma_f32_16x16x32_bf16 v[8:11], v[158:161], v[206:209], v[8:11]
	v_mfma_f32_16x16x32_bf16 v[60:63], v[154:157], v[186:189], v[60:63]
	v_mfma_f32_16x16x32_bf16 v[56:59], v[162:165], v[186:189], v[56:59]
	v_mfma_f32_16x16x32_bf16 v[44:47], v[154:157], v[194:197], v[44:47]
	v_mfma_f32_16x16x32_bf16 v[40:43], v[162:165], v[194:197], v[40:43]
	v_mfma_f32_16x16x32_bf16 v[28:31], v[154:157], v[202:205], v[28:31]
	v_mfma_f32_16x16x32_bf16 v[24:27], v[162:165], v[202:205], v[24:27]
	v_mfma_f32_16x16x32_bf16 v[12:15], v[154:157], v[210:213], v[12:15]
	v_mfma_f32_16x16x32_bf16 v[8:11], v[162:165], v[210:213], v[8:11]
	s_setprio 0
	s_setprio 1
	v_mfma_f32_16x16x32_bf16 v[52:55], v[166:169], v[182:185], v[52:55]
	v_mfma_f32_16x16x32_bf16 v[48:51], v[174:177], v[182:185], v[48:51]
	v_mfma_f32_16x16x32_bf16 v[36:39], v[166:169], v[190:193], v[36:39]
	v_mfma_f32_16x16x32_bf16 v[32:35], v[174:177], v[190:193], v[32:35]
	v_mfma_f32_16x16x32_bf16 v[20:23], v[166:169], v[198:201], v[20:23]
	v_mfma_f32_16x16x32_bf16 v[16:19], v[174:177], v[198:201], v[16:19]
	v_mfma_f32_16x16x32_bf16 v[4:7], v[166:169], v[206:209], v[4:7]
	v_mfma_f32_16x16x32_bf16 v[0:3], v[174:177], v[206:209], v[0:3]
	v_mfma_f32_16x16x32_bf16 v[52:55], v[170:173], v[186:189], v[52:55]
	v_mfma_f32_16x16x32_bf16 v[48:51], v[178:181], v[186:189], v[48:51]
	v_mfma_f32_16x16x32_bf16 v[36:39], v[170:173], v[194:197], v[36:39]
	v_mfma_f32_16x16x32_bf16 v[32:35], v[178:181], v[194:197], v[32:35]
	v_mfma_f32_16x16x32_bf16 v[20:23], v[170:173], v[202:205], v[20:23]
	v_mfma_f32_16x16x32_bf16 v[16:19], v[178:181], v[202:205], v[16:19]
	v_mfma_f32_16x16x32_bf16 v[4:7], v[170:173], v[210:213], v[4:7]
	v_mfma_f32_16x16x32_bf16 v[0:3], v[178:181], v[210:213], v[0:3]
	s_setprio 0
	s_barrier
	s_add_i32 s65, 0, 0x18000
	s_add_i32 s66, 0, 0x1c000
	v_add_u32_e32 v162, s65, v149
	v_add_u32_e32 v178, s66, v149
	ds_read_b128 v[144:147], v162
	ds_read_b128 v[154:157], v162 offset:1024
	ds_read_b128 v[158:161], v162 offset:2048
	ds_read_b128 v[162:165], v162 offset:3072
	ds_read_b128 v[166:169], v178
	ds_read_b128 v[170:173], v178 offset:1024
	ds_read_b128 v[174:177], v178 offset:2048
	ds_read_b128 v[178:181], v178 offset:3072
	s_add_u32 s54, s54, 0x100000
	s_addc_u32 s55, s55, 0
	s_mov_b32 m0, s34
	v_lshl_add_u64 v[226:227], s[54:55], 0, v[128:129]
	ds_read_b128 v[182:185], v153 offset:32768
	ds_read_b128 v[186:189], v153 offset:33792
	ds_read_b128 v[190:193], v153 offset:34816
	ds_read_b128 v[194:197], v153 offset:35840
	ds_read_b128 v[198:201], v153 offset:36864
	ds_read_b128 v[202:205], v153 offset:37888
	ds_read_b128 v[206:209], v153 offset:38912
	ds_read_b128 v[210:213], v153 offset:39936
	global_load_lds_dwordx4 v[226:227], off
	v_lshl_add_u64 v[226:227], s[54:55], 0, v[132:133]
	s_mov_b32 m0, s35
	s_nop 0
	global_load_lds_dwordx4 v[226:227], off
	s_waitcnt vmcnt(8)
	s_waitcnt lgkmcnt(0)
	s_barrier
	s_setprio 1
	s_waitcnt lgkmcnt(0)
	v_mfma_f32_16x16x32_bf16 v[124:127], v[144:147], v[182:185], v[124:127]
	v_mfma_f32_16x16x32_bf16 v[120:123], v[158:161], v[182:185], v[120:123]
	v_mfma_f32_16x16x32_bf16 v[108:111], v[144:147], v[190:193], v[108:111]
	v_mfma_f32_16x16x32_bf16 v[104:107], v[158:161], v[190:193], v[104:107]
	v_mfma_f32_16x16x32_bf16 v[92:95], v[144:147], v[198:201], v[92:95]
	v_mfma_f32_16x16x32_bf16 v[88:91], v[158:161], v[198:201], v[88:91]
	v_mfma_f32_16x16x32_bf16 v[76:79], v[144:147], v[206:209], v[76:79]
	v_mfma_f32_16x16x32_bf16 v[72:75], v[158:161], v[206:209], v[72:75]
	v_mfma_f32_16x16x32_bf16 v[124:127], v[154:157], v[186:189], v[124:127]
	v_mfma_f32_16x16x32_bf16 v[120:123], v[162:165], v[186:189], v[120:123]
	v_mfma_f32_16x16x32_bf16 v[108:111], v[154:157], v[194:197], v[108:111]
	v_mfma_f32_16x16x32_bf16 v[104:107], v[162:165], v[194:197], v[104:107]
	v_mfma_f32_16x16x32_bf16 v[92:95], v[154:157], v[202:205], v[92:95]
	v_mfma_f32_16x16x32_bf16 v[88:91], v[162:165], v[202:205], v[88:91]
	v_mfma_f32_16x16x32_bf16 v[76:79], v[154:157], v[210:213], v[76:79]
	v_mfma_f32_16x16x32_bf16 v[72:75], v[162:165], v[210:213], v[72:75]
	s_setprio 0
	s_setprio 1
	v_mfma_f32_16x16x32_bf16 v[116:119], v[166:169], v[182:185], v[116:119]
	v_mfma_f32_16x16x32_bf16 v[112:115], v[174:177], v[182:185], v[112:115]
	v_mfma_f32_16x16x32_bf16 v[100:103], v[166:169], v[190:193], v[100:103]
	v_mfma_f32_16x16x32_bf16 v[96:99], v[174:177], v[190:193], v[96:99]
	v_mfma_f32_16x16x32_bf16 v[84:87], v[166:169], v[198:201], v[84:87]
	v_mfma_f32_16x16x32_bf16 v[80:83], v[174:177], v[198:201], v[80:83]
	v_mfma_f32_16x16x32_bf16 v[68:71], v[166:169], v[206:209], v[68:71]
	v_mfma_f32_16x16x32_bf16 v[64:67], v[174:177], v[206:209], v[64:67]
	v_mfma_f32_16x16x32_bf16 v[116:119], v[170:173], v[186:189], v[116:119]
	v_mfma_f32_16x16x32_bf16 v[112:115], v[178:181], v[186:189], v[112:115]
	v_mfma_f32_16x16x32_bf16 v[100:103], v[170:173], v[194:197], v[100:103]
	v_mfma_f32_16x16x32_bf16 v[96:99], v[178:181], v[194:197], v[96:99]
	v_mfma_f32_16x16x32_bf16 v[84:87], v[170:173], v[202:205], v[84:87]
	v_mfma_f32_16x16x32_bf16 v[80:83], v[178:181], v[202:205], v[80:83]
	v_mfma_f32_16x16x32_bf16 v[68:71], v[170:173], v[210:213], v[68:71]
	v_mfma_f32_16x16x32_bf16 v[64:67], v[178:181], v[210:213], v[64:67]
	s_setprio 0
	s_barrier
; #define PG8_STAGE(bufoff, gbase, voff) do { _Pragma("unroll") for (int _i = 0; _i < 2; ++_i) \
;         __builtin_amdgcn_global_load_lds((const unsigned*)((const char*)(gbase) + (voff)[_i]), (PG8_LAS unsigned*)(lds + (bufoff) + ldsw + _i * 8192), 16, 0, 0); } while (0)
; #define PG8_LDA(dst, b, h) do { _Pragma("unroll") for (int m = 0; m < 4; ++m) _Pragma("unroll") for (int k = 0; k < 2; ++k) dst[m][k] = *(const PG8_LAS bf16x8*)(lds + PG8_SA(b, h) + aoff + m * 2048 + k * 1024); } while (0)
; #define PG8_MMA(ai, bj, At, Bt) do { __builtin_amdgcn_s_setprio(1); _Pragma("unroll") for (int m = 0; m < 4; ++m) _Pragma("unroll") for (int n = 0; n < 2; ++n) _Pragma("unroll") for (int k = 0; k < 2; ++k) \
;         acc[ai][bj][m][n] = __builtin_amdgcn_mfma_f32_16x16x32_bf16(Bt[n][k], At[m][k], acc[ai][bj][m][n], 0, 0, 0); __builtin_amdgcn_s_setprio(0); } while (0)
; #define PG8_WAIT_V(n) asm volatile("s_waitcnt vmcnt(" #n ")" ::: "memory")
; #define PG8_WAIT_L(n) asm volatile("s_waitcnt lgkmcnt(" #n ")" ::: "memory")
; #define PG8_BAR __builtin_amdgcn_s_barrier()
; #define PG8_SCHED __builtin_amdgcn_sched_barrier(0)
;     __device__ __forceinline__ void operator()(const f32x4 (&acc)[2][2][4][2], const Unit& u, int wr, int wc, int fr, int fq) const {
;         const int row0 = u.pm * BM + wr * 64 + fr, col0 = u.pn * BM + wc * 32 + 8 * fq;
; #pragma unroll
;         for (int ai = 0; ai < 2; ++ai)
; #pragma unroll
;             for (int m = 0; m < 4; ++m) { const size_t row = (size_t)(row0 + ai * HALF + m * 16); float s = 0.f;
; #pragma unroll
;                 for (int bj = 0; bj < 2; ++bj) { const size_t off = row * 1024 + col0 + bj * HALF; const u32x4 h = __builtin_nontemporal_load((const u32x4*)(HB + off));
; template <class Epi, class Sched, bool ALIGN_EPI = false, bool SP2 = false>
; __device__ __forceinline__ void gemm_phase(PG8_LAS unsigned char* lds, const Gemm g, const Sched& S, const Epi& E, const int wave_s) {
;     ...
;             PG8_WAIT_V(8); PG8_WAIT_L(0); PG8_BAR; PG8_MMA(0, 0, At, B0); PG8_MMA(0, 1, At, B1); PG8_BAR; PG8_SCHED;
;             PG8_LDA(At, 1, 1); PG8_STAGE(PG8_SB(1, 0), b3, voffB); PG8_STAGE(PG8_SB(1, 1), b3 + hB, voffB); PG8_STAGE(PG8_SA(1, 0), a3, voffA);
;             PG8_WAIT_V(8); PG8_WAIT_L(0); PG8_BAR; PG8_MMA(1, 0, At, B0); PG8_MMA(1, 1, At, B1); PG8_BAR; PG8_SCHED;
	s_add_i32 s54, s65, s11
	v_lshl_add_u64 v[218:219], v[218:219], 0, s[18:19]
	s_mov_b32 m0, s54
	ds_read_b128 v[182:185], v153 offset:49152
	ds_read_b128 v[186:189], v153 offset:50176
	ds_read_b128 v[190:193], v153 offset:51200
	ds_read_b128 v[194:197], v153 offset:52224
	ds_read_b128 v[198:201], v153 offset:53248
	ds_read_b128 v[202:205], v153 offset:54272
	ds_read_b128 v[206:209], v153 offset:55296
	ds_read_b128 v[210:213], v153 offset:56320
	global_load_lds_dwordx4 v[218:219], off
	s_add_i32 m0, s54, 0x2000
	s_add_u32 s50, s50, 0x100080
	v_lshl_add_u64 v[218:219], v[220:221], 0, s[18:19]
	s_addc_u32 s51, s51, 0
	s_add_i32 s54, s66, s11
	global_load_lds_dwordx4 v[218:219], off
	v_lshl_add_u64 v[218:219], s[50:51], 0, v[130:131]
	s_mov_b32 m0, s54
	s_nop 0
	global_load_lds_dwordx4 v[218:219], off
	v_lshl_add_u64 v[218:219], s[50:51], 0, v[134:135]
	s_add_i32 m0, s54, 0x2000
	s_nop 0
	global_load_lds_dwordx4 v[218:219], off
	v_lshl_add_u64 v[218:219], v[222:223], 0, s[18:19]
	s_mov_b32 m0, s56
	s_nop 0
	global_load_lds_dwordx4 v[218:219], off
	v_lshl_add_u64 v[218:219], v[224:225], 0, s[18:19]
	s_mov_b32 m0, s57
	s_nop 0
	global_load_lds_dwordx4 v[218:219], off
	s_waitcnt vmcnt(8)
	s_waitcnt lgkmcnt(0)
	s_barrier
	s_setprio 1
	s_waitcnt lgkmcnt(0)
	v_mfma_f32_16x16x32_bf16 v[60:63], v[144:147], v[182:185], v[60:63]
	v_mfma_f32_16x16x32_bf16 v[56:59], v[158:161], v[182:185], v[56:59]
	v_mfma_f32_16x16x32_bf16 v[44:47], v[144:147], v[190:193], v[44:47]
	v_mfma_f32_16x16x32_bf16 v[40:43], v[158:161], v[190:193], v[40:43]
	v_mfma_f32_16x16x32_bf16 v[28:31], v[144:147], v[198:201], v[28:31]
	v_mfma_f32_16x16x32_bf16 v[24:27], v[158:161], v[198:201], v[24:27]
	v_mfma_f32_16x16x32_bf16 v[12:15], v[144:147], v[206:209], v[12:15]
	v_mfma_f32_16x16x32_bf16 v[8:11], v[158:161], v[206:209], v[8:11]
	v_mfma_f32_16x16x32_bf16 v[60:63], v[154:157], v[186:189], v[60:63]
	v_mfma_f32_16x16x32_bf16 v[56:59], v[162:165], v[186:189], v[56:59]
	v_mfma_f32_16x16x32_bf16 v[44:47], v[154:157], v[194:197], v[44:47]
	v_mfma_f32_16x16x32_bf16 v[40:43], v[162:165], v[194:197], v[40:43]
	v_mfma_f32_16x16x32_bf16 v[28:31], v[154:157], v[202:205], v[28:31]
	v_mfma_f32_16x16x32_bf16 v[24:27], v[162:165], v[202:205], v[24:27]
	v_mfma_f32_16x16x32_bf16 v[12:15], v[154:157], v[210:213], v[12:15]
	v_mfma_f32_16x16x32_bf16 v[8:11], v[162:165], v[210:213], v[8:11]
	s_setprio 0
	s_setprio 1
	v_mfma_f32_16x16x32_bf16 v[52:55], v[166:169], v[182:185], v[52:55]
	v_mfma_f32_16x16x32_bf16 v[48:51], v[174:177], v[182:185], v[48:51]
	v_mfma_f32_16x16x32_bf16 v[36:39], v[166:169], v[190:193], v[36:39]
	v_mfma_f32_16x16x32_bf16 v[32:35], v[174:177], v[190:193], v[32:35]
	v_mfma_f32_16x16x32_bf16 v[20:23], v[166:169], v[198:201], v[20:23]
	v_mfma_f32_16x16x32_bf16 v[16:19], v[174:177], v[198:201], v[16:19]
	v_mfma_f32_16x16x32_bf16 v[4:7], v[166:169], v[206:209], v[4:7]
	v_mfma_f32_16x16x32_bf16 v[0:3], v[174:177], v[206:209], v[0:3]
	v_mfma_f32_16x16x32_bf16 v[52:55], v[170:173], v[186:189], v[52:55]
	v_mfma_f32_16x16x32_bf16 v[48:51], v[178:181], v[186:189], v[48:51]
	v_mfma_f32_16x16x32_bf16 v[36:39], v[170:173], v[194:197], v[36:39]
	v_mfma_f32_16x16x32_bf16 v[32:35], v[178:181], v[194:197], v[32:35]
	v_mfma_f32_16x16x32_bf16 v[20:23], v[170:173], v[202:205], v[20:23]
	v_mfma_f32_16x16x32_bf16 v[16:19], v[178:181], v[202:205], v[16:19]
	v_mfma_f32_16x16x32_bf16 v[4:7], v[170:173], v[210:213], v[4:7]
	v_mfma_f32_16x16x32_bf16 v[0:3], v[178:181], v[210:213], v[0:3]
	s_setprio 0
	s_cmpk_lg_i32 s64, 60
	s_cbranch_scc1 .Learly_LBB0_859
	v_lshl_add_u32 v146, s46, 8, v148
	v_ashrrev_i32_e32 v147, 31, v146
	v_lshl_or_b32 v144, s44, 8, v150
	v_lshlrev_b64 v[154:155], 11, v[146:147]
	v_ashrrev_i32_e32 v145, 31, v144
	v_lshl_add_u64 v[154:155], s[14:15], 0, v[154:155]
	v_lshl_add_u64 v[162:163], v[144:145], 1, v[154:155]
	global_load_dwordx4 v[172:175], v[162:163], off nt
	global_load_dwordx4 v[176:179], v[162:163], off offset:256 nt
	s_mov_b32 s99, 0
	s_mov_b32 s98, 0x8000
	v_lshl_add_u64 v[212:213], v[162:163], 0, s[98:99]
	global_load_dwordx4 v[180:183], v[212:213], off nt
	global_load_dwordx4 v[184:187], v[212:213], off offset:256 nt
	s_mov_b32 s98, 0x10000
	v_lshl_add_u64 v[212:213], v[162:163], 0, s[98:99]
	global_load_dwordx4 v[188:191], v[212:213], off nt
	global_load_dwordx4 v[192:195], v[212:213], off offset:256 nt
	s_mov_b32 s98, 0x18000
	v_lshl_add_u64 v[212:213], v[162:163], 0, s[98:99]
	global_load_dwordx4 v[196:199], v[212:213], off nt
	global_load_dwordx4 v[200:203], v[212:213], off offset:256 nt
	s_mov_b32 s98, 0x40000
	v_lshl_add_u64 v[212:213], v[162:163], 0, s[98:99]
	global_load_dwordx4 v[204:207], v[212:213], off nt
	global_load_dwordx4 v[208:211], v[212:213], off offset:256 nt
	s_mov_b32 s98, 0x48000
	v_lshl_add_u64 v[212:213], v[162:163], 0, s[98:99]
	global_load_dwordx4 v[228:231], v[212:213], off nt
	global_load_dwordx4 v[232:235], v[212:213], off offset:256 nt
	s_mov_b32 s98, 0x50000
	v_lshl_add_u64 v[212:213], v[162:163], 0, s[98:99]
	global_load_dwordx4 v[236:239], v[212:213], off nt
	global_load_dwordx4 v[240:243], v[212:213], off offset:256 nt
	s_mov_b32 s98, 0x58000
	v_lshl_add_u64 v[212:213], v[162:163], 0, s[98:99]
	global_load_dwordx4 v[244:247], v[212:213], off nt
	global_load_dwordx4 v[248:251], v[212:213], off offset:256 nt
; __device__ __forceinline__ float bflo(unsigned w) { return __uint_as_float(w << 16); }
; __device__ __forceinline__ float bfhi(unsigned w) { return __uint_as_float(w & 0xffff0000u); }
; __device__ __forceinline__ u32x4 pk8(const f32x4 a, const f32x4 b) { u32x4 w; w.x = pkbf(a[0], a[1]); w.y = pkbf(a[2], a[3]); w.z = pkbf(b[0], b[1]); w.w = pkbf(b[2], b[3]); return w; }
; __device__ __forceinline__ float sumsq4(const f32x4 a) { return (a[0] * a[0] + a[1] * a[1]) + (a[2] * a[2] + a[3] * a[3]); }
; #define PG8_BAR __builtin_amdgcn_s_barrier()
;     __device__ __forceinline__ void operator()(const f32x4 (&acc)[2][2][4][2], const Unit& u, int wr, int wc, int fr, int fq) const {
;     ...
;             for (int m = 0; m < 4; ++m) { const size_t row = (size_t)(row0 + ai * HALF + m * 16); float s = 0.f;
; #pragma unroll
;                 for (int bj = 0; bj < 2; ++bj) { const size_t off = row * 1024 + col0 + bj * HALF; const u32x4 h = __builtin_nontemporal_load((const u32x4*)(HB + off));
;                     f32x4 a = acc[ai][bj][m][0], b = acc[ai][bj][m][1];
;                     a[0] += bflo(h.x); a[1] += bfhi(h.x); a[2] += bflo(h.y); a[3] += bfhi(h.y); b[0] += bflo(h.z); b[1] += bfhi(h.z); b[2] += bflo(h.w); b[3] += bfhi(h.w);
;                     s += sumsq4(a) + sumsq4(b); *(u32x4*)(HO + off) = pk8(a, b); }
;                 s += __shfl_xor(s, 16); s += __shfl_xor(s, 32);
;                 if (fq == 0) unsafeAtomicAdd(ss + row, s); }
; template <class Epi, class Sched, bool ALIGN_EPI = false, bool SP2 = false>
; __device__ __forceinline__ void gemm_phase(PG8_LAS unsigned char* lds, const Gemm g, const Sched& S, const Epi& E, const int wave_s) {
;     ...
;         if constexpr (ALIGN_EPI) { if (wr == 0) PG8_BAR; }
.Learly_LBB0_859:
	s_barrier
	s_add_i32 s64, s64, 2
	s_add_u32 s48, s48, 0x100
	s_addc_u32 s49, s49, 0
	s_add_u32 s45, s45, 0x100
	s_addc_u32 s63, s63, 0
	s_cmp_gt_u32 s64, 61
	s_cbranch_scc0 .LBB0_856
	s_and_b64 vcc, exec, s[20:21]
	s_cbranch_vccz .LBB0_859
	s_barrier
.LBB0_859:
	s_waitcnt vmcnt(14)
	v_mov_b32_e32 v154, v172
	v_mov_b32_e32 v155, v173
	v_mov_b32_e32 v156, v174
	v_mov_b32_e32 v157, v175
	v_mov_b32_e32 v158, v176
	v_mov_b32_e32 v159, v177
	v_mov_b32_e32 v160, v178
	v_mov_b32_e32 v161, v179
	v_lshlrev_b32_e32 v164, 16, v154
	v_and_b32_e32 v165, 0xffff0000, v154
	v_lshlrev_b32_e32 v154, 16, v155
	v_and_b32_e32 v155, 0xffff0000, v155
	v_lshlrev_b32_e32 v166, 16, v156
	v_and_b32_e32 v167, 0xffff0000, v156
	v_lshlrev_b32_e32 v156, 16, v157
	v_and_b32_e32 v157, 0xffff0000, v157
	v_lshlrev_b32_e32 v168, 16, v158
	v_and_b32_e32 v169, 0xffff0000, v158
	v_lshlrev_b32_e32 v158, 16, v159
	v_and_b32_e32 v159, 0xffff0000, v159
	v_lshlrev_b32_e32 v170, 16, v160
	v_and_b32_e32 v171, 0xffff0000, v160
	v_lshlrev_b32_e32 v160, 16, v161
	v_and_b32_e32 v161, 0xffff0000, v161
	v_pk_add_f32 v[124:125], v[124:125], v[164:165]
	v_pk_add_f32 v[126:127], v[126:127], v[154:155]
	v_pk_add_f32 v[120:121], v[120:121], v[166:167]
	v_pk_add_f32 v[122:123], v[122:123], v[156:157]
	v_pk_add_f32 v[116:117], v[116:117], v[168:169]
	v_pk_add_f32 v[118:119], v[118:119], v[158:159]
	v_pk_add_f32 v[154:155], v[112:113], v[170:171]
	v_pk_add_f32 v[156:157], v[114:115], v[160:161]
	v_pk_mul_f32 v[114:115], v[124:125], v[124:125]
	v_pk_mul_f32 v[158:159], v[126:127], v[126:127]
	v_pk_mul_f32 v[160:161], v[120:121], v[120:121]
	v_pk_mul_f32 v[164:165], v[122:123], v[122:123]
	v_cvt_pk_bf16_f32 v112, v124, v125
	v_cvt_pk_bf16_f32 v113, v126, v127
	v_pk_mul_f32 v[124:125], v[116:117], v[116:117]
	v_pk_mul_f32 v[126:127], v[118:119], v[118:119]
	v_pk_mul_f32 v[166:167], v[154:155], v[154:155]
	v_pk_mul_f32 v[168:169], v[156:157], v[156:157]
	v_add_f32_e32 v166, v166, v167
	v_add_f32_e32 v168, v168, v169
	v_add_f32_e32 v126, v126, v127
	v_add_f32_e32 v124, v124, v125
	v_add_f32_e32 v125, v164, v165
	v_add_f32_e32 v127, v160, v161
	v_add_f32_e32 v158, v158, v159
	v_add_f32_e32 v114, v114, v115
	v_add_f32_e32 v115, v166, v168
	v_add_f32_e32 v124, v124, v126
	v_add_f32_e32 v125, v127, v125
	v_add_f32_e32 v114, v114, v158
	v_add_f32_e32 v115, v124, v115
	v_add_f32_e32 v114, v114, v125
	v_add_f32_e32 v124, v114, v115
	ds_bpermute_b32 v125, v215, v124
	v_cvt_pk_bf16_f32 v114, v120, v121
	v_cvt_pk_bf16_f32 v115, v122, v123
	global_store_dwordx4 v[162:163], v[112:115], off
	s_waitcnt lgkmcnt(0)
	s_nop 0
	v_add_f32_e32 v112, v124, v125
	ds_bpermute_b32 v113, v216, v112
	v_cvt_pk_bf16_f32 v114, v116, v117
	v_cvt_pk_bf16_f32 v115, v118, v119
	v_cvt_pk_bf16_f32 v116, v154, v155
	v_cvt_pk_bf16_f32 v117, v156, v157
	global_store_dwordx4 v[162:163], v[114:117], off offset:256
	s_and_saveexec_b64 s[44:45], s[2:3]
	s_cbranch_execz .LBB0_861
	v_lshl_add_u64 v[114:115], v[146:147], 2, s[0:1]
	s_waitcnt lgkmcnt(0)
	v_add_f32_e32 v112, v112, v113
	global_atomic_add_f32 v[114:115], v112, off
